# MLA attention: one static priority raise for waves 4-7 (reset at the phase end)
# baseline (speedup 1.0000x reference)
; template <int VAR>
; __device__ __forceinline__ void attn_unit(LAS unsigned char* lds, const Desc& d, int u) {
;     ...
;     else if (VAR == 1) { const int nqb = T / 256, qb = u % nqb; head = (u / nqb) & 15; seq = u / (nqb * 16); qpos0 = qb * 256 + 32 * wid;
;         t_lo = 0; t_hi = T / 64; wt_lo = t_lo; wt_hi = t_hi; qcol = head * 96; kcol = head * 128; vcol = head * 128 + 64; }
;     else {
;         const int rows = T / 64, nrb = rows / 4, rb = u % nrb; head = (u / nrb) & 15; seq = u / (nrb * 16); grow = 4 * rb + 2 * (wid >> 2); qpos0 = 0;
;         int k0 = grow - 4; k0 = k0 < 0 ? 0 : k0; k0 = k0 > rows - 9 ? rows - 9 : k0; wt_lo = k0; wt_hi = k0 + 9;
;         int a = 4 * rb - 4; a = a < 0 ? 0 : a; a = a > rows - 9 ? rows - 9 : a; int b = 4 * rb - 2; b = b < 0 ? 0 : b; b = b > rows - 9 ? rows - 9 : b; t_lo = a; t_hi = b + 9;
;         kc0 = 16 * (wid & 3) - 8; kc0 = kc0 < 0 ? 0 : kc0; kc0 = kc0 > 32 ? 32 : kc0;
;         qrow_l = grow + (r32 >> 4); qcol_l = 16 * (wid & 3) + (r32 & 15);
;         rs_l = qrow_l - 4; rs_l = rs_l < 0 ? 0 : rs_l; rs_l = rs_l > rows - 8 ? rows - 8 : rs_l;
;         qcol = head * 64; kcol = 1024 + head * 64; vcol = 2048 + head * 64; }
;     const int qtok_l = VAR == 2 ? qrow_l * 64 + qcol_l : qpos0 + r32;
;     const size_t rowb = (size_t)seq * T;
;     const int skey = tid >> 3, sc = tid & 7, skey2 = tid >> 2, sc2 = tid & 3;
;     const bf16_t* kg = d.K + (rowb + skey) * d.ldk + kcol + sc * 8;
;     const bf16_t* vg = d.V + (rowb + skey) * d.ldv + vcol + sc * 8;
;     const bf16_t* k2g = (VAR == 1) ? d.K2 + (rowb + skey2) * d.ldk2 + 640 + sc2 * 8 : nullptr;
;     const float* ktab = (VAR == 0) ? d.tab + ((size_t)skey * 32 + 8 * (sc & 3)) * 2 : nullptr;
;     const float ksgn = sc < 4 ? -1.f : 1.f;
;     const int klds = skey * KSTR + sc * 16, vlds = ((skey >> 3) * 2 + (sc >> 2)) * 512 + (skey & 7) * 64 + (sc & 3) * 16, k2lds = skey2 * KSTR + 128 + sc2 * 16;
;     u32x4 kreg[2], vreg[1], k2reg[2]; f32x4 kcs[2][4]; k2reg[0] = k2reg[1] = (u32x4){0, 0, 0, 0};
.LBB0_1121:
	s_abs_i32 s7, s1
	v_readlane_b32 s8, v255, 4
	s_mul_hi_u32 s8, s7, s8
	v_readlane_b32 s12, v255, 8
	s_mul_i32 s9, s8, s12
	s_sub_i32 s9, s7, s9
	s_ashr_i32 s6, s1, 31
	s_add_i32 s10, s8, 1
	s_sub_i32 s11, s9, s12
	s_cmp_ge_u32 s9, s12
	s_cselect_b32 s8, s10, s8
	s_cselect_b32 s9, s11, s9
	s_add_i32 s10, s8, 1
	s_cmp_ge_u32 s9, s12
	s_cselect_b32 s8, s10, s8
	v_readlane_b32 s10, v255, 6
	s_mul_hi_u32 s10, s7, s10
	v_readlane_b32 s13, v255, 5
	s_xor_b32 s8, s8, s6
	s_mul_i32 s11, s10, s13
	s_sub_i32 s9, s8, s6
	s_sub_i32 s7, s7, s11
	s_and_b32 s8, s9, 15
	s_add_i32 s11, s10, 1
	s_sub_i32 s12, s7, s13
	s_cmp_ge_u32 s7, s13
	s_cselect_b32 s10, s11, s10
	s_cselect_b32 s7, s12, s7
	s_add_i32 s11, s10, 1
	s_cmp_ge_u32 s7, s13
	s_cselect_b32 s7, s11, s10
	s_xor_b32 s7, s7, s6
	v_mov_b32_e32 v70, v203
	s_sub_i32 s6, s7, s6
	s_ashr_i32 s7, s6, 31
	v_readlane_b32 s10, v255, 3
	v_ashrrev_i32_e32 v50, 3, v70
	s_lshl_b64 s[6:7], s[6:7], s10
	v_ashrrev_i32_e32 v51, 31, v50
	v_lshl_add_u64 v[2:3], s[6:7], 0, v[50:51]
	v_readlane_b32 s10, v253, 33
	v_lshlrev_b64 v[200:201], 12, v[2:3]
	v_readlane_b32 s11, v253, 34
	v_and_b32_e32 v52, 7, v70
	s_lshl_b32 s36, s8, 8
	v_lshl_add_u64 v[2:3], s[10:11], 0, v[200:201]
	v_lshl_add_u64 v[2:3], v[2:3], 0, s[36:37]
	v_lshlrev_b32_e32 v0, 4, v52
	v_lshl_add_u64 v[78:79], v[2:3], 0, v[0:1]
	global_load_dwordx4 v[30:33], v[78:79], off
	v_ashrrev_i32_e32 v6, 2, v70
	v_ashrrev_i32_e32 v7, 31, v6
	v_lshl_add_u64 v[214:215], s[6:7], 0, v[6:7]
	v_mov_b64_e32 v[2:3], s[4:5]
	s_movk_i32 s13, 0x600
	v_and_b32_e32 v4, 3, v70
	v_mad_u64_u32 v[2:3], s[10:11], v214, s13, v[2:3]
	v_mad_i32_i24 v3, v215, s13, v3
	v_lshlrev_b32_e32 v212, 4, v4
	v_mov_b32_e32 v213, v1
	v_lshl_add_u64 v[2:3], v[2:3], 0, v[212:213]
	s_mov_b64 s[10:11], 0x500
	v_lshl_add_u64 v[80:81], v[2:3], 0, s[10:11]
	s_movk_i32 s10, 0x100
	v_readfirstlane_b32 s12, v70
	v_cmp_gt_i32_e64 s[40:41], s10, v70
	s_cmp_lt_u32 s12, 0x100
	s_cbranch_scc1 .Lmla_prio_done
	s_setprio 1
.Lmla_prio_done:
	v_mov_b32_e32 v2, v1
	v_mov_b32_e32 v3, v1
	v_mov_b32_e32 v4, v1
	v_mov_b32_e32 v5, v1
	s_and_saveexec_b64 s[10:11], s[40:41]
	s_cbranch_execz .LBB0_1123
	global_load_dwordx4 v[2:5], v[80:81], off

; __device__ __forceinline__ void xcd_barrier(const XcdBarrier& b) {
;     asm volatile("s_waitcnt vmcnt(0)" ::: "memory");
;     __syncthreads();
;     if (threadIdx.x == 0) {
;         unsigned* bar = b.bar;
;         __builtin_amdgcn_s_waitcnt(0);
;         unsigned nloc = b.st[0], nx = b.st[1];
;         if (nloc == 0u) { xcd_barrier_complete(bar, b.x, nloc, nx); b.st[0] = nloc; b.st[1] = nx; }
; __global__ void __launch_bounds__(512, 2) fwd_kernel(Params p) {
;     ...
;                 xcd_barrier(xbar);
.LBB0_1173:
	s_setprio 0
	s_waitcnt vmcnt(0)
	s_barrier
	s_mov_b64 s[6:7], exec
	v_readlane_b32 s8, v252, 2
	v_readlane_b32 s9, v252, 3
	s_and_b64 s[8:9], s[6:7], s[8:9]
	v_readlane_b32 s36, v254, 63
	s_mov_b64 exec, s[8:9]
	s_cbranch_execz .LBB0_1225
	v_readlane_b32 s1, v254, 6
	s_waitcnt vmcnt(0) expcnt(0) lgkmcnt(0)
	s_nop 0
	v_mov_b32_e32 v0, s1
	ds_read_b32 v3, v0
	v_readlane_b32 s1, v254, 7
	s_waitcnt lgkmcnt(0)
	v_cmp_ne_u32_e32 vcc, 0, v3
	v_mov_b32_e32 v0, s1
	ds_read_b32 v2, v0
	s_cbranch_vccnz .LBB0_1189
	s_mov_b32 s1, 1
	s_branch .LBB0_1177
